# two-group stagger: workgroups 128-255 start INB, OUTPROJ and WO half a unit period late so HBM-bound epilogue bursts of one half overlap the K-loops of the other
# baseline (speedup 1.0000x reference)
.LBB0_270:
	s_lshr_b32 s98, s33, 7
	s_mul_i32 s98, s98, 1700
	s_memrealtime s[100:101]
	s_waitcnt lgkmcnt(0)
	s_add_u32 s99, s100, s98

.LBB0_345:
	s_lshr_b32 s98, s33, 7
	s_mul_i32 s98, s98, 2100
	s_memrealtime s[100:101]
	s_waitcnt lgkmcnt(0)
	s_add_u32 s99, s100, s98
